# P8 conv epilogue: removed 96 dead zero-initialisations of DPP destinations fully overwritten by row_ror moves (EXEC full), hazard pads re-established
# speedup vs baseline: 1.0106x; 1.0106x over previous
.LBB0_768:
	v_pk_mul_f32 v[210:211], v[148:149], v[208:209] op_sel_hi:[1,0]
	s_waitcnt lgkmcnt(0)
	v_mov_b32_dpp v172, v164 row_shr:1 row_mask:0xf bank_mask:0xf
	v_mov_b32_dpp v173, v165 row_shr:1 row_mask:0xf bank_mask:0xf
	v_mov_b32_dpp v148, v210 row_ror:15 row_mask:0xf bank_mask:0xf
	v_mov_b32_dpp v149, v211 row_ror:15 row_mask:0xf bank_mask:0xf
	s_waitcnt vmcnt(0)
	v_pk_fma_f32 v[172:173], v[80:81], v[172:173], v[84:85]
	v_pk_mul_f32 v[206:207], v[150:151], v[208:209] op_sel_hi:[1,0]
	v_mov_b32_dpp v174, v166 row_shr:1 row_mask:0xf bank_mask:0xf
	v_mov_b32_dpp v175, v167 row_shr:1 row_mask:0xf bank_mask:0xf
	v_mov_b32_dpp v148, v164 row_shl:1 row_mask:0xf bank_mask:0xf
	v_mov_b32_dpp v149, v165 row_shl:1 row_mask:0xf bank_mask:0xf
	v_pk_fma_f32 v[172:173], v[164:165], v[76:77], v[172:173]
	v_mov_b32_dpp v150, v206 row_ror:15 row_mask:0xf bank_mask:0xf
	v_mov_b32_dpp v151, v207 row_ror:15 row_mask:0xf bank_mask:0xf
	v_pk_fma_f32 v[174:175], v[82:83], v[174:175], v[86:87]
	v_pk_fma_f32 v[148:149], v[72:73], v[148:149], v[172:173]
	v_mov_b32_dpp v150, v166 row_shl:1 row_mask:0xf bank_mask:0xf
	v_mov_b32_dpp v151, v167 row_shl:1 row_mask:0xf bank_mask:0xf
	v_pk_fma_f32 v[174:175], v[166:167], v[78:79], v[174:175]
	v_pk_mul_f32 v[172:173], v[148:149], v[148:149]
	v_pk_fma_f32 v[150:151], v[74:75], v[150:151], v[174:175]
	v_pk_mul_f32 v[172:173], v[148:149], v[172:173]
	v_pk_mul_f32 v[174:175], v[150:151], v[150:151]
	v_pk_fma_f32 v[172:173], v[172:173], s[70:71], v[148:149] op_sel_hi:[1,0,1]
	v_pk_mul_f32 v[174:175], v[150:151], v[174:175]
	v_pk_mul_f32 v[172:173], v[172:173], s[72:73] op_sel_hi:[1,0]
	v_pk_fma_f32 v[174:175], v[174:175], s[70:71], v[150:151] op_sel_hi:[1,0,1]
	v_min_f32_e32 v172, 0x41e6d4ca, v172
	v_pk_mul_f32 v[174:175], v[174:175], s[72:73] op_sel_hi:[1,0]
	v_exp_f32_e32 v233, v172
	v_min_f32_e32 v172, 0x41e6d4ca, v173
	v_exp_f32_e32 v232, v172
	v_min_f32_e32 v172, 0x41e6d4ca, v174
	v_exp_f32_e32 v173, v172
	v_min_f32_e32 v172, 0x41e6d4ca, v175
	v_exp_f32_e32 v172, v172
	v_mov_b32_e32 v230, v212
	v_mov_b32_e32 v231, v212
	v_pk_mul_f32 v[146:147], v[146:147], v[230:231]
	v_pk_mul_f32 v[144:145], v[144:145], v[212:213]
	v_pk_mul_f32 v[138:139], v[138:139], v[230:231]
	v_pk_mul_f32 v[136:137], v[136:137], v[212:213]
	v_pk_add_f32 v[212:213], v[232:233], 1.0 op_sel_hi:[1,0]
	v_pk_add_f32 v[230:231], v[172:173], 1.0 op_sel_hi:[1,0]
	v_mul_f32_e32 v232, v213, v212
	v_mul_f32_e32 v233, v231, v230
	v_pk_mul_f32 v[174:175], v[140:141], v[208:209] op_sel_hi:[1,0]
	v_mul_f32_e32 v172, v232, v233
	v_rcp_f32_e32 v199, v172
	v_mov_b32_dpp v168, v160 row_shr:1 row_mask:0xf bank_mask:0xf
	v_mov_b32_dpp v169, v161 row_shr:1 row_mask:0xf bank_mask:0xf
	v_pk_fma_f32 v[168:169], v[64:65], v[168:169], v[68:69]
	v_mul_f32_e32 v140, v232, v199
	v_pk_mul_f32 v[230:231], v[230:231], v[140:141] op_sel_hi:[1,0]
	v_pk_mul_f32 v[172:173], v[142:143], v[208:209] op_sel_hi:[1,0]
	v_mov_b32_dpp v140, v174 row_ror:15 row_mask:0xf bank_mask:0xf
	v_mov_b32_dpp v141, v175 row_ror:15 row_mask:0xf bank_mask:0xf
	v_mov_b32_dpp v170, v162 row_shr:1 row_mask:0xf bank_mask:0xf
	v_mov_b32_dpp v171, v163 row_shr:1 row_mask:0xf bank_mask:0xf
	v_mov_b32_dpp v140, v160 row_shl:1 row_mask:0xf bank_mask:0xf
	v_mov_b32_dpp v141, v161 row_shl:1 row_mask:0xf bank_mask:0xf
	v_pk_fma_f32 v[168:169], v[160:161], v[60:61], v[168:169]
	v_mov_b32_dpp v142, v172 row_ror:15 row_mask:0xf bank_mask:0xf
	v_mov_b32_dpp v143, v173 row_ror:15 row_mask:0xf bank_mask:0xf
	v_pk_fma_f32 v[170:171], v[66:67], v[170:171], v[70:71]
	v_pk_fma_f32 v[140:141], v[56:57], v[140:141], v[168:169]
	v_mov_b32_dpp v142, v162 row_shl:1 row_mask:0xf bank_mask:0xf
	v_mov_b32_dpp v143, v163 row_shl:1 row_mask:0xf bank_mask:0xf
	v_pk_fma_f32 v[170:171], v[162:163], v[62:63], v[170:171]
	v_pk_mul_f32 v[168:169], v[140:141], v[140:141]
	v_pk_fma_f32 v[142:143], v[58:59], v[142:143], v[170:171]
	v_pk_mul_f32 v[168:169], v[140:141], v[168:169]
	v_pk_mul_f32 v[170:171], v[142:143], v[142:143]
	v_pk_fma_f32 v[168:169], v[168:169], s[70:71], v[140:141] op_sel_hi:[1,0,1]
	v_pk_mul_f32 v[170:171], v[142:143], v[170:171]
	v_pk_mul_f32 v[168:169], v[168:169], s[72:73] op_sel_hi:[1,0]
	v_pk_fma_f32 v[170:171], v[170:171], s[70:71], v[142:143] op_sel_hi:[1,0,1]
	v_min_f32_e32 v168, 0x41e6d4ca, v168
	v_mul_f32_e32 v234, v233, v199
	v_pk_mul_f32 v[170:171], v[170:171], s[72:73] op_sel_hi:[1,0]
	v_exp_f32_e32 v233, v168
	v_min_f32_e32 v168, 0x41e6d4ca, v169
	v_exp_f32_e32 v232, v168
	v_min_f32_e32 v168, 0x41e6d4ca, v170
	v_exp_f32_e32 v169, v168
	v_min_f32_e32 v168, 0x41e6d4ca, v171
	v_exp_f32_e32 v168, v168
	v_pk_mul_f32 v[170:171], v[212:213], v[234:235] op_sel_hi:[1,0]
	v_pk_add_f32 v[212:213], v[232:233], 1.0 op_sel_hi:[1,0]
	v_pk_mul_f32 v[170:171], v[148:149], v[170:171]
	v_pk_add_f32 v[168:169], v[168:169], 1.0 op_sel_hi:[1,0]
	v_mov_b32_e32 v232, v213
	v_mov_b32_e32 v233, v169
	v_mov_b32_e32 v234, v212
	v_mov_b32_e32 v235, v168
	v_pk_mul_f32 v[232:233], v[232:233], v[234:235]
	v_pk_mul_f32 v[170:171], v[144:145], v[170:171]
	v_mul_f32_e32 v199, v232, v233
	v_rcp_f32_e32 v199, v199
	v_add_u32_e32 v197, s11, v217
	v_pk_mul_f32 v[230:231], v[150:151], v[230:231]
	s_lshl_b32 s12, s10, 1
	v_mul_f32_e32 v234, v233, v199
	v_mul_f32_e32 v232, v232, v199
	v_pk_mul_f32 v[212:213], v[212:213], v[234:235] op_sel_hi:[1,0]
	v_pk_mul_f32 v[168:169], v[168:169], v[232:233] op_sel_hi:[1,0]
	v_pk_mul_f32 v[212:213], v[140:141], v[212:213]
	v_pk_mul_f32 v[168:169], v[142:143], v[168:169]
	v_pk_mul_f32 v[212:213], v[136:137], v[212:213]
	v_pk_mul_f32 v[232:233], v[138:139], v[168:169]
	v_cvt_pk_bf16_f32 v168, v170, v171
	v_cvt_pk_bf16_f32 v170, v212, v213
	v_mov_b64_e32 v[212:213], s[86:87]
	s_mul_i32 s15, s10, 0x10800
	v_pk_mul_f32 v[230:231], v[146:147], v[230:231]
	v_mad_i64_i32 v[212:213], s[10:11], v197, s90, v[212:213]
	s_mul_hi_i32 s16, s12, 0x8400
	v_cvt_pk_bf16_f32 v169, v230, v231
	v_cvt_pk_bf16_f32 v171, v232, v233
	v_lshl_add_u64 v[212:213], v[192:193], 1, v[212:213]
	global_store_dwordx4 v[212:213], v[168:171], off
	s_and_saveexec_b64 s[10:11], s[40:41]
	s_cbranch_execz .LBB0_770
	s_add_u32 s24, s4, s15
	s_addc_u32 s25, s5, s16
	v_lshl_add_u64 v[168:169], v[192:193], 2, s[24:25]
	global_store_dwordx4 v[168:169], v[148:151], off
	s_nop 1
	v_add_co_u32_e32 v148, vcc, 0x2000, v168
	s_nop 1
	v_addc_co_u32_e32 v149, vcc, 0, v169, vcc
	v_add_co_u32_e32 v150, vcc, 0x5000, v168
	global_store_dwordx4 v[148:149], v[164:167], off offset:3072
	s_nop 0
	v_addc_co_u32_e32 v151, vcc, 0, v169, vcc
	global_store_dwordx4 v[150:151], v[144:147], off offset:2048
	global_store_dwordx4 v[168:169], v[140:143], off offset:16
	global_store_dwordx4 v[148:149], v[160:163], off offset:3088
	global_store_dwordx4 v[150:151], v[136:139], off offset:2064
.LBB0_770:
	s_or_b64 exec, exec, s[10:11]
	v_mov_b32_e32 v209, v208
	v_pk_mul_f32 v[140:141], v[116:117], v[208:209]
	v_pk_mul_f32 v[116:117], v[120:121], v[202:203] op_sel_hi:[1,0]
	v_mov_b32_e32 v120, v204
	v_mov_b32_e32 v121, v204
	v_pk_mul_f32 v[102:103], v[102:103], v[120:121]
	v_pk_mul_f32 v[98:99], v[98:99], v[120:121]
	v_mov_b32_e32 v136, v208
	v_mov_b32_e32 v137, v208
	v_mov_b32_dpp v120, v164 row_ror:1 row_mask:0xf bank_mask:0xf
	v_mov_b32_dpp v121, v165 row_ror:1 row_mask:0xf bank_mask:0xf
	v_pk_mul_f32 v[138:139], v[118:119], v[136:137]
	v_pk_mul_f32 v[136:137], v[114:115], v[136:137]
	v_pk_mul_f32 v[118:119], v[126:127], v[202:203] op_sel_hi:[1,0]
	v_pk_mul_f32 v[124:125], v[124:125], v[202:203] op_sel_hi:[1,0]
	v_pk_mul_f32 v[114:115], v[122:123], v[202:203] op_sel_hi:[1,0]
	v_mov_b32_dpp v120, v210 row_shr:1 row_mask:0xf bank_mask:0xf
	v_mov_b32_dpp v121, v211 row_shr:1 row_mask:0xf bank_mask:0xf
	v_mov_b32_dpp v122, v166 row_ror:1 row_mask:0xf bank_mask:0xf
	v_mov_b32_dpp v123, v167 row_ror:1 row_mask:0xf bank_mask:0xf
	v_mov_b32_dpp v126, v124 row_ror:15 row_mask:0xf bank_mask:0xf
	v_mov_b32_dpp v127, v125 row_ror:15 row_mask:0xf bank_mask:0xf
	v_pk_fma_f32 v[120:121], v[80:81], v[120:121], v[84:85]
	v_mov_b32_dpp v122, v206 row_shr:1 row_mask:0xf bank_mask:0xf
	v_mov_b32_dpp v123, v207 row_shr:1 row_mask:0xf bank_mask:0xf
	v_mov_b32_dpp v126, v210 row_shl:1 row_mask:0xf bank_mask:0xf
	v_mov_b32_dpp v127, v211 row_shl:1 row_mask:0xf bank_mask:0xf
	v_pk_fma_f32 v[120:121], v[210:211], v[76:77], v[120:121]
	v_mov_b32_dpp v142, v118 row_ror:15 row_mask:0xf bank_mask:0xf
	v_mov_b32_dpp v143, v119 row_ror:15 row_mask:0xf bank_mask:0xf
	v_pk_fma_f32 v[122:123], v[82:83], v[122:123], v[86:87]
	v_pk_fma_f32 v[120:121], v[72:73], v[126:127], v[120:121]
	v_mov_b32_dpp v142, v206 row_shl:1 row_mask:0xf bank_mask:0xf
	v_mov_b32_dpp v143, v207 row_shl:1 row_mask:0xf bank_mask:0xf
	v_pk_fma_f32 v[122:123], v[206:207], v[78:79], v[122:123]
	v_pk_mul_f32 v[126:127], v[120:121], v[120:121]
	v_pk_fma_f32 v[122:123], v[74:75], v[142:143], v[122:123]
	v_pk_mul_f32 v[126:127], v[120:121], v[126:127]
	v_pk_mul_f32 v[142:143], v[122:123], v[122:123]
	v_pk_fma_f32 v[126:127], v[126:127], s[70:71], v[120:121] op_sel_hi:[1,0,1]
	v_pk_mul_f32 v[142:143], v[122:123], v[142:143]
	v_pk_mul_f32 v[126:127], v[126:127], s[72:73] op_sel_hi:[1,0]
	v_pk_fma_f32 v[142:143], v[142:143], s[70:71], v[122:123] op_sel_hi:[1,0,1]
	v_min_f32_e32 v126, 0x41e6d4ca, v126
	v_pk_mul_f32 v[142:143], v[142:143], s[72:73] op_sel_hi:[1,0]
	v_exp_f32_e32 v145, v126
	v_min_f32_e32 v126, 0x41e6d4ca, v127
	v_exp_f32_e32 v144, v126
	v_min_f32_e32 v126, 0x41e6d4ca, v142
	v_exp_f32_e32 v127, v126
	v_min_f32_e32 v126, 0x41e6d4ca, v143
	v_exp_f32_e32 v126, v126
	v_pk_add_f32 v[142:143], v[144:145], 1.0 op_sel_hi:[1,0]
	v_pk_mul_f32 v[112:113], v[112:113], v[208:209]
	v_pk_add_f32 v[126:127], v[126:127], 1.0 op_sel_hi:[1,0]
	v_mul_f32_e32 v144, v143, v142
	v_mul_f32_e32 v145, v127, v126
	v_or_b32_e32 v148, 16, v197
	v_mul_f32_e32 v146, v144, v145
	v_rcp_f32_e32 v147, v146
	v_pk_mul_f32 v[108:109], v[108:109], v[202:203] op_sel_hi:[1,0]
	v_pk_mul_f32 v[110:111], v[110:111], v[202:203] op_sel_hi:[1,0]
	v_pk_mul_f32 v[106:107], v[106:107], v[202:203] op_sel_hi:[1,0]
	v_mul_f32_e32 v144, v144, v147
	v_mul_f32_e32 v146, v145, v147
	v_pk_mul_f32 v[126:127], v[126:127], v[144:145] op_sel_hi:[1,0]
	v_pk_mul_f32 v[142:143], v[142:143], v[146:147] op_sel_hi:[1,0]
	v_pk_mul_f32 v[122:123], v[122:123], v[126:127]
	v_pk_mul_f32 v[120:121], v[120:121], v[142:143]
	v_mov_b32_dpp v126, v160 row_ror:1 row_mask:0xf bank_mask:0xf
	v_mov_b32_dpp v127, v161 row_ror:1 row_mask:0xf bank_mask:0xf
	v_pk_mul_f32 v[122:123], v[138:139], v[122:123]
	v_pk_mul_f32 v[120:121], v[140:141], v[120:121]
	v_mov_b32_dpp v126, v174 row_shr:1 row_mask:0xf bank_mask:0xf
	v_mov_b32_dpp v127, v175 row_shr:1 row_mask:0xf bank_mask:0xf
	v_mov_b32_dpp v138, v162 row_ror:1 row_mask:0xf bank_mask:0xf
	v_mov_b32_dpp v139, v163 row_ror:1 row_mask:0xf bank_mask:0xf
	v_mov_b32_dpp v140, v116 row_ror:15 row_mask:0xf bank_mask:0xf
	v_mov_b32_dpp v141, v117 row_ror:15 row_mask:0xf bank_mask:0xf
	v_pk_fma_f32 v[126:127], v[64:65], v[126:127], v[68:69]
	v_mov_b32_dpp v138, v172 row_shr:1 row_mask:0xf bank_mask:0xf
	v_mov_b32_dpp v139, v173 row_shr:1 row_mask:0xf bank_mask:0xf
	v_mov_b32_dpp v140, v174 row_shl:1 row_mask:0xf bank_mask:0xf
	v_mov_b32_dpp v141, v175 row_shl:1 row_mask:0xf bank_mask:0xf
	v_pk_fma_f32 v[126:127], v[174:175], v[60:61], v[126:127]
	v_mov_b32_dpp v142, v114 row_ror:15 row_mask:0xf bank_mask:0xf
	v_mov_b32_dpp v143, v115 row_ror:15 row_mask:0xf bank_mask:0xf
	v_pk_fma_f32 v[138:139], v[66:67], v[138:139], v[70:71]
	v_pk_fma_f32 v[126:127], v[56:57], v[140:141], v[126:127]
	v_mov_b32_dpp v142, v172 row_shl:1 row_mask:0xf bank_mask:0xf
	v_mov_b32_dpp v143, v173 row_shl:1 row_mask:0xf bank_mask:0xf
	v_pk_fma_f32 v[138:139], v[172:173], v[62:63], v[138:139]
	v_pk_mul_f32 v[140:141], v[126:127], v[126:127]
	v_pk_fma_f32 v[138:139], v[58:59], v[142:143], v[138:139]
	v_pk_mul_f32 v[140:141], v[126:127], v[140:141]
	v_pk_mul_f32 v[142:143], v[138:139], v[138:139]
	v_pk_fma_f32 v[140:141], v[140:141], s[70:71], v[126:127] op_sel_hi:[1,0,1]
	v_pk_mul_f32 v[142:143], v[138:139], v[142:143]
	v_pk_mul_f32 v[140:141], v[140:141], s[72:73] op_sel_hi:[1,0]
	v_pk_fma_f32 v[142:143], v[142:143], s[70:71], v[138:139] op_sel_hi:[1,0,1]
	v_min_f32_e32 v140, 0x41e6d4ca, v140
	v_pk_mul_f32 v[142:143], v[142:143], s[72:73] op_sel_hi:[1,0]
	v_exp_f32_e32 v145, v140
	v_min_f32_e32 v140, 0x41e6d4ca, v141
	v_exp_f32_e32 v144, v140
	v_min_f32_e32 v140, 0x41e6d4ca, v142
	v_exp_f32_e32 v141, v140
	v_min_f32_e32 v140, 0x41e6d4ca, v143
	v_exp_f32_e32 v140, v140
	v_pk_add_f32 v[142:143], v[144:145], 1.0 op_sel_hi:[1,0]
	v_pk_mul_f32 v[104:105], v[104:105], v[202:203] op_sel_hi:[1,0]
	v_pk_add_f32 v[140:141], v[140:141], 1.0 op_sel_hi:[1,0]
	v_mul_f32_e32 v144, v143, v142
	v_mul_f32_e32 v145, v141, v140
	v_mov_b32_dpp v156, v132 row_shl:1 row_mask:0xf bank_mask:0xf
	v_mul_f32_e32 v146, v144, v145
	v_rcp_f32_e32 v147, v146
	v_mov_b32_dpp v157, v133 row_shl:1 row_mask:0xf bank_mask:0xf
	v_mov_b32_dpp v158, v134 row_shl:1 row_mask:0xf bank_mask:0xf
	v_mov_b32_dpp v159, v135 row_shl:1 row_mask:0xf bank_mask:0xf
	v_mul_f32_e32 v146, v145, v147
	v_mul_f32_e32 v144, v144, v147
	v_pk_mul_f32 v[140:141], v[140:141], v[144:145] op_sel_hi:[1,0]
	v_pk_mul_f32 v[142:143], v[142:143], v[146:147] op_sel_hi:[1,0]
	v_pk_mul_f32 v[138:139], v[138:139], v[140:141]
	v_pk_mul_f32 v[126:127], v[126:127], v[142:143]
	v_pk_mul_f32 v[140:141], v[136:137], v[138:139]
	v_pk_mul_f32 v[112:113], v[112:113], v[126:127]
	v_cvt_pk_bf16_f32 v136, v120, v121
	v_mov_b64_e32 v[120:121], s[86:87]
	v_cvt_pk_bf16_f32 v137, v122, v123
	v_cvt_pk_bf16_f32 v138, v112, v113
	v_mad_i64_i32 v[122:123], s[10:11], v148, s90, v[120:121]
	v_lshlrev_b64 v[112:113], 1, v[192:193]
	v_cvt_pk_bf16_f32 v139, v140, v141
	v_lshl_add_u64 v[122:123], v[122:123], 0, v[112:113]
	global_store_dwordx4 v[122:123], v[136:139], off
	s_nop 0
	v_mov_b32_dpp v122, v210 row_ror:1 row_mask:0xf bank_mask:0xf
	v_mov_b32_dpp v123, v211 row_ror:1 row_mask:0xf bank_mask:0xf
	s_nop 0
	v_mov_b32_dpp v122, v124 row_shr:1 row_mask:0xf bank_mask:0xf
	v_mov_b32_dpp v123, v125 row_shr:1 row_mask:0xf bank_mask:0xf
	v_mov_b32_dpp v126, v206 row_ror:1 row_mask:0xf bank_mask:0xf
	v_mov_b32_dpp v127, v207 row_ror:1 row_mask:0xf bank_mask:0xf
	v_mov_b32_dpp v136, v132 row_ror:15 row_mask:0xf bank_mask:0xf
	v_mov_b32_dpp v137, v133 row_ror:15 row_mask:0xf bank_mask:0xf
	v_pk_fma_f32 v[122:123], v[80:81], v[122:123], v[84:85]
	v_mov_b32_dpp v126, v118 row_shr:1 row_mask:0xf bank_mask:0xf
	v_mov_b32_dpp v127, v119 row_shr:1 row_mask:0xf bank_mask:0xf
	v_mov_b32_dpp v136, v124 row_shl:1 row_mask:0xf bank_mask:0xf
	v_mov_b32_dpp v137, v125 row_shl:1 row_mask:0xf bank_mask:0xf
	v_pk_fma_f32 v[122:123], v[124:125], v[76:77], v[122:123]
	v_mov_b32_dpp v138, v134 row_ror:15 row_mask:0xf bank_mask:0xf
	v_mov_b32_dpp v139, v135 row_ror:15 row_mask:0xf bank_mask:0xf
	v_pk_fma_f32 v[126:127], v[82:83], v[126:127], v[86:87]
	v_pk_fma_f32 v[122:123], v[72:73], v[136:137], v[122:123]
	v_mov_b32_dpp v138, v118 row_shl:1 row_mask:0xf bank_mask:0xf
	v_mov_b32_dpp v139, v119 row_shl:1 row_mask:0xf bank_mask:0xf
	v_pk_fma_f32 v[126:127], v[118:119], v[78:79], v[126:127]
	v_pk_mul_f32 v[136:137], v[122:123], v[122:123]
	v_pk_fma_f32 v[126:127], v[74:75], v[138:139], v[126:127]
	v_pk_mul_f32 v[136:137], v[122:123], v[136:137]
	v_pk_mul_f32 v[138:139], v[126:127], v[126:127]
	v_pk_fma_f32 v[136:137], v[136:137], s[70:71], v[122:123] op_sel_hi:[1,0,1]
	v_pk_mul_f32 v[138:139], v[126:127], v[138:139]
	v_pk_mul_f32 v[136:137], v[136:137], s[72:73] op_sel_hi:[1,0]
	v_pk_fma_f32 v[138:139], v[138:139], s[70:71], v[126:127] op_sel_hi:[1,0,1]
	v_min_f32_e32 v136, 0x41e6d4ca, v136
	v_pk_mul_f32 v[138:139], v[138:139], s[72:73] op_sel_hi:[1,0]
	v_exp_f32_e32 v141, v136
	v_min_f32_e32 v136, 0x41e6d4ca, v137
	v_exp_f32_e32 v140, v136
	v_min_f32_e32 v136, 0x41e6d4ca, v138
	v_exp_f32_e32 v137, v136
	v_min_f32_e32 v136, 0x41e6d4ca, v139
	v_exp_f32_e32 v136, v136
	v_pk_add_f32 v[138:139], v[140:141], 1.0 op_sel_hi:[1,0]
	v_or_b32_e32 v144, 32, v197
	v_pk_add_f32 v[136:137], v[136:137], 1.0 op_sel_hi:[1,0]
	v_mul_f32_e32 v140, v139, v138
	v_mul_f32_e32 v141, v137, v136
	v_pk_mul_f32 v[100:101], v[100:101], v[204:205]
	v_mul_f32_e32 v142, v140, v141
	v_rcp_f32_e32 v143, v142
	v_mov_b32_dpp v152, v128 row_shl:1 row_mask:0xf bank_mask:0xf
	v_mov_b32_dpp v153, v129 row_shl:1 row_mask:0xf bank_mask:0xf
	v_mov_b32_dpp v154, v130 row_shl:1 row_mask:0xf bank_mask:0xf
	v_mul_f32_e32 v142, v141, v143
	v_pk_mul_f32 v[138:139], v[138:139], v[142:143] op_sel_hi:[1,0]
	v_mul_f32_e32 v140, v140, v143
	v_pk_mul_f32 v[122:123], v[122:123], v[138:139]
	v_pk_mul_f32 v[136:137], v[136:137], v[140:141] op_sel_hi:[1,0]
	v_pk_mul_f32 v[108:109], v[108:109], v[122:123]
	v_pk_mul_f32 v[126:127], v[126:127], v[136:137]
	v_mov_b32_dpp v122, v174 row_ror:1 row_mask:0xf bank_mask:0xf
	v_mov_b32_dpp v123, v175 row_ror:1 row_mask:0xf bank_mask:0xf
	v_pk_mul_f32 v[110:111], v[110:111], v[126:127]
	v_mov_b32_dpp v122, v116 row_shr:1 row_mask:0xf bank_mask:0xf
	v_mov_b32_dpp v123, v117 row_shr:1 row_mask:0xf bank_mask:0xf
	v_mov_b32_dpp v126, v172 row_ror:1 row_mask:0xf bank_mask:0xf
	v_mov_b32_dpp v127, v173 row_ror:1 row_mask:0xf bank_mask:0xf
	v_mov_b32_dpp v136, v128 row_ror:15 row_mask:0xf bank_mask:0xf
	v_mov_b32_dpp v137, v129 row_ror:15 row_mask:0xf bank_mask:0xf
	v_pk_fma_f32 v[122:123], v[64:65], v[122:123], v[68:69]
	v_mov_b32_dpp v126, v114 row_shr:1 row_mask:0xf bank_mask:0xf
	v_mov_b32_dpp v127, v115 row_shr:1 row_mask:0xf bank_mask:0xf
	v_mov_b32_dpp v136, v116 row_shl:1 row_mask:0xf bank_mask:0xf
	v_mov_b32_dpp v137, v117 row_shl:1 row_mask:0xf bank_mask:0xf
	v_pk_fma_f32 v[122:123], v[116:117], v[60:61], v[122:123]
	v_mov_b32_dpp v138, v130 row_ror:15 row_mask:0xf bank_mask:0xf
	v_mov_b32_dpp v139, v131 row_ror:15 row_mask:0xf bank_mask:0xf
	v_pk_fma_f32 v[126:127], v[66:67], v[126:127], v[70:71]
	v_pk_fma_f32 v[122:123], v[56:57], v[136:137], v[122:123]
	v_mov_b32_dpp v138, v114 row_shl:1 row_mask:0xf bank_mask:0xf
	v_mov_b32_dpp v139, v115 row_shl:1 row_mask:0xf bank_mask:0xf
	v_pk_fma_f32 v[126:127], v[114:115], v[62:63], v[126:127]
	v_pk_mul_f32 v[136:137], v[122:123], v[122:123]
	v_pk_fma_f32 v[126:127], v[58:59], v[138:139], v[126:127]
	v_pk_mul_f32 v[136:137], v[122:123], v[136:137]
	v_pk_mul_f32 v[138:139], v[126:127], v[126:127]
	v_pk_fma_f32 v[136:137], v[136:137], s[70:71], v[122:123] op_sel_hi:[1,0,1]
	v_pk_mul_f32 v[138:139], v[126:127], v[138:139]
	v_pk_mul_f32 v[136:137], v[136:137], s[72:73] op_sel_hi:[1,0]
	v_pk_fma_f32 v[138:139], v[138:139], s[70:71], v[126:127] op_sel_hi:[1,0,1]
	v_min_f32_e32 v136, 0x41e6d4ca, v136
	v_pk_mul_f32 v[138:139], v[138:139], s[72:73] op_sel_hi:[1,0]
	v_exp_f32_e32 v141, v136
	v_min_f32_e32 v136, 0x41e6d4ca, v137
	v_exp_f32_e32 v140, v136
	v_min_f32_e32 v136, 0x41e6d4ca, v138
	v_exp_f32_e32 v137, v136
	v_min_f32_e32 v136, 0x41e6d4ca, v139
	v_exp_f32_e32 v136, v136
	v_pk_add_f32 v[138:139], v[140:141], 1.0 op_sel_hi:[1,0]
	v_mov_b32_dpp v155, v131 row_shl:1 row_mask:0xf bank_mask:0xf
	v_pk_add_f32 v[136:137], v[136:137], 1.0 op_sel_hi:[1,0]
	v_mul_f32_e32 v140, v139, v138
	v_mul_f32_e32 v141, v137, v136
	v_pk_mul_f32 v[96:97], v[96:97], v[204:205]
	v_mul_f32_e32 v142, v140, v141
	v_rcp_f32_e32 v143, v142
	s_or_b32 s14, s12, 1
	s_mul_hi_i32 s12, s14, 0x8400
	s_mul_i32 s14, s14, 0x8400
	v_mul_f32_e32 v142, v141, v143
	v_mul_f32_e32 v140, v140, v143
	v_pk_mul_f32 v[136:137], v[136:137], v[140:141] op_sel_hi:[1,0]
	v_pk_mul_f32 v[138:139], v[138:139], v[142:143] op_sel_hi:[1,0]
	v_pk_mul_f32 v[126:127], v[126:127], v[136:137]
	v_pk_mul_f32 v[122:123], v[122:123], v[138:139]
	v_pk_mul_f32 v[126:127], v[106:107], v[126:127]
	v_pk_mul_f32 v[106:107], v[104:105], v[122:123]
	v_cvt_pk_bf16_f32 v104, v108, v109
	v_mad_i64_i32 v[108:109], s[10:11], v144, s90, v[120:121]
	v_cvt_pk_bf16_f32 v105, v110, v111
	v_cvt_pk_bf16_f32 v106, v106, v107
	v_cvt_pk_bf16_f32 v107, v126, v127
	v_lshl_add_u64 v[108:109], v[108:109], 0, v[112:113]
	global_store_dwordx4 v[108:109], v[104:107], off
	v_or_b32_e32 v136, 48, v197
	s_nop 0
	v_mov_b32_dpp v104, v124 row_ror:1 row_mask:0xf bank_mask:0xf
	v_mov_b32_dpp v105, v125 row_ror:1 row_mask:0xf bank_mask:0xf
	s_nop 0
	v_mov_b32_dpp v104, v132 row_shr:1 row_mask:0xf bank_mask:0xf
	v_mov_b32_dpp v105, v133 row_shr:1 row_mask:0xf bank_mask:0xf
	v_mov_b32_dpp v106, v118 row_ror:1 row_mask:0xf bank_mask:0xf
	v_mov_b32_dpp v107, v119 row_ror:1 row_mask:0xf bank_mask:0xf
	v_pk_fma_f32 v[104:105], v[80:81], v[104:105], v[84:85]
	v_mov_b32_dpp v106, v134 row_shr:1 row_mask:0xf bank_mask:0xf
	v_mov_b32_dpp v107, v135 row_shr:1 row_mask:0xf bank_mask:0xf
	v_pk_fma_f32 v[104:105], v[132:133], v[76:77], v[104:105]
	v_pk_fma_f32 v[106:107], v[82:83], v[106:107], v[86:87]
	v_pk_fma_f32 v[104:105], v[72:73], v[156:157], v[104:105]
	v_pk_fma_f32 v[106:107], v[134:135], v[78:79], v[106:107]
	v_pk_mul_f32 v[108:109], v[104:105], v[104:105]
	v_pk_fma_f32 v[106:107], v[74:75], v[158:159], v[106:107]
	v_pk_mul_f32 v[108:109], v[104:105], v[108:109]
	v_pk_mul_f32 v[110:111], v[106:107], v[106:107]
	v_pk_fma_f32 v[108:109], v[108:109], s[70:71], v[104:105] op_sel_hi:[1,0,1]
	v_pk_mul_f32 v[110:111], v[106:107], v[110:111]
	v_pk_mul_f32 v[108:109], v[108:109], s[72:73] op_sel_hi:[1,0]
	v_pk_fma_f32 v[110:111], v[110:111], s[70:71], v[106:107] op_sel_hi:[1,0,1]
	v_min_f32_e32 v108, 0x41e6d4ca, v108
	v_pk_mul_f32 v[110:111], v[110:111], s[72:73] op_sel_hi:[1,0]
	v_exp_f32_e32 v119, v108
	v_min_f32_e32 v108, 0x41e6d4ca, v109
	v_exp_f32_e32 v118, v108
	v_min_f32_e32 v108, 0x41e6d4ca, v110
	v_exp_f32_e32 v109, v108
	v_min_f32_e32 v108, 0x41e6d4ca, v111
	v_exp_f32_e32 v108, v108
	v_pk_add_f32 v[110:111], v[118:119], 1.0 op_sel_hi:[1,0]
	v_pk_add_f32 v[108:109], v[108:109], 1.0 op_sel_hi:[1,0]
	v_mul_f32_e32 v118, v111, v110
	v_mul_f32_e32 v119, v109, v108
	s_nop 0
	v_mul_f32_e32 v122, v118, v119
	v_rcp_f32_e32 v123, v122
	s_nop 0
	v_mul_f32_e32 v118, v118, v123
	v_pk_mul_f32 v[108:109], v[108:109], v[118:119] op_sel_hi:[1,0]
	v_mul_f32_e32 v122, v119, v123
	v_pk_mul_f32 v[108:109], v[106:107], v[108:109]
	v_pk_mul_f32 v[110:111], v[110:111], v[122:123] op_sel_hi:[1,0]
	v_pk_mul_f32 v[118:119], v[102:103], v[108:109]
	v_pk_mul_f32 v[110:111], v[104:105], v[110:111]
	v_mov_b32_dpp v108, v116 row_ror:1 row_mask:0xf bank_mask:0xf
	v_mov_b32_dpp v109, v117 row_ror:1 row_mask:0xf bank_mask:0xf
	v_pk_mul_f32 v[122:123], v[100:101], v[110:111]
	v_mov_b32_dpp v108, v128 row_shr:1 row_mask:0xf bank_mask:0xf
	v_mov_b32_dpp v109, v129 row_shr:1 row_mask:0xf bank_mask:0xf
	v_mov_b32_dpp v110, v114 row_ror:1 row_mask:0xf bank_mask:0xf
	v_mov_b32_dpp v111, v115 row_ror:1 row_mask:0xf bank_mask:0xf
	v_pk_fma_f32 v[108:109], v[64:65], v[108:109], v[68:69]
	v_mov_b32_dpp v110, v130 row_shr:1 row_mask:0xf bank_mask:0xf
	v_mov_b32_dpp v111, v131 row_shr:1 row_mask:0xf bank_mask:0xf
	v_pk_fma_f32 v[108:109], v[128:129], v[60:61], v[108:109]
	v_pk_fma_f32 v[110:111], v[66:67], v[110:111], v[70:71]
	v_pk_fma_f32 v[108:109], v[56:57], v[152:153], v[108:109]
	v_pk_fma_f32 v[110:111], v[130:131], v[62:63], v[110:111]
	v_pk_mul_f32 v[114:115], v[108:109], v[108:109]
	v_pk_fma_f32 v[110:111], v[58:59], v[154:155], v[110:111]
	v_pk_mul_f32 v[114:115], v[108:109], v[114:115]
	v_pk_mul_f32 v[116:117], v[110:111], v[110:111]
	v_pk_fma_f32 v[114:115], v[114:115], s[70:71], v[108:109] op_sel_hi:[1,0,1]
	v_pk_mul_f32 v[116:117], v[110:111], v[116:117]
	v_pk_mul_f32 v[114:115], v[114:115], s[72:73] op_sel_hi:[1,0]
	v_pk_fma_f32 v[116:117], v[116:117], s[70:71], v[110:111] op_sel_hi:[1,0,1]
	v_min_f32_e32 v114, 0x41e6d4ca, v114
	v_pk_mul_f32 v[116:117], v[116:117], s[72:73] op_sel_hi:[1,0]
	v_exp_f32_e32 v125, v114
	v_min_f32_e32 v114, 0x41e6d4ca, v115
	v_exp_f32_e32 v124, v114
	v_min_f32_e32 v114, 0x41e6d4ca, v116
	v_exp_f32_e32 v115, v114
	v_min_f32_e32 v114, 0x41e6d4ca, v117
	v_exp_f32_e32 v114, v114
	v_pk_add_f32 v[116:117], v[124:125], 1.0 op_sel_hi:[1,0]
	v_pk_add_f32 v[114:115], v[114:115], 1.0 op_sel_hi:[1,0]
	v_mul_f32_e32 v124, v117, v116
	v_mul_f32_e32 v125, v115, v114
	s_nop 0
	v_mul_f32_e32 v126, v124, v125
	v_rcp_f32_e32 v127, v126
	s_nop 0
	v_mul_f32_e32 v126, v125, v127
	v_mul_f32_e32 v124, v124, v127
	v_pk_mul_f32 v[114:115], v[114:115], v[124:125] op_sel_hi:[1,0]
	v_pk_mul_f32 v[116:117], v[116:117], v[126:127] op_sel_hi:[1,0]
	v_pk_mul_f32 v[114:115], v[110:111], v[114:115]
	v_pk_mul_f32 v[116:117], v[108:109], v[116:117]
	v_pk_mul_f32 v[124:125], v[98:99], v[114:115]
	v_pk_mul_f32 v[116:117], v[96:97], v[116:117]
	v_cvt_pk_bf16_f32 v115, v118, v119
	v_mad_i64_i32 v[118:119], s[10:11], v136, s90, v[120:121]
	v_cvt_pk_bf16_f32 v114, v122, v123
	v_cvt_pk_bf16_f32 v116, v116, v117
	v_cvt_pk_bf16_f32 v117, v124, v125
	v_lshl_add_u64 v[118:119], v[118:119], 0, v[112:113]
	global_store_dwordx4 v[118:119], v[114:117], off
	s_and_saveexec_b64 s[10:11], s[58:59]
	s_cbranch_execz .LBB0_772
	s_add_u32 s24, s4, s14
	s_addc_u32 s25, s5, s12
	v_lshl_add_u64 v[114:115], v[192:193], 2, s[24:25]
	global_store_dwordx4 v[114:115], v[104:107], off
	s_nop 1
	v_add_co_u32_e32 v104, vcc, 0x2000, v114
	s_nop 1
	v_addc_co_u32_e32 v105, vcc, 0, v115, vcc
	v_add_co_u32_e32 v106, vcc, 0x5000, v114
	global_store_dwordx4 v[104:105], v[132:135], off offset:3072
	s_nop 0
	v_addc_co_u32_e32 v107, vcc, 0, v115, vcc
	global_store_dwordx4 v[106:107], v[100:103], off offset:2048
	global_store_dwordx4 v[114:115], v[108:111], off offset:16
	global_store_dwordx4 v[104:105], v[128:131], off offset:3088
	global_store_dwordx4 v[106:107], v[96:99], off offset:2064

.LBB0_780:
	v_pk_mul_f32 v[116:117], v[52:53], v[198:199] op_sel_hi:[1,0]
	s_waitcnt lgkmcnt(0)
	v_mov_b32_dpp v108, v92 row_shr:1 row_mask:0xf bank_mask:0xf
	v_mov_b32_dpp v109, v93 row_shr:1 row_mask:0xf bank_mask:0xf
	v_mov_b32_dpp v52, v116 row_ror:15 row_mask:0xf bank_mask:0xf
	v_mov_b32_dpp v53, v117 row_ror:15 row_mask:0xf bank_mask:0xf
	v_pk_fma_f32 v[108:109], v[80:81], v[108:109], v[84:85]
	v_pk_mul_f32 v[114:115], v[54:55], v[198:199] op_sel_hi:[1,0]
	v_mov_b32_dpp v110, v94 row_shr:1 row_mask:0xf bank_mask:0xf
	v_mov_b32_dpp v111, v95 row_shr:1 row_mask:0xf bank_mask:0xf
	v_mov_b32_dpp v52, v92 row_shl:1 row_mask:0xf bank_mask:0xf
	v_mov_b32_dpp v53, v93 row_shl:1 row_mask:0xf bank_mask:0xf
	v_pk_fma_f32 v[108:109], v[92:93], v[76:77], v[108:109]
	v_mov_b32_dpp v54, v114 row_ror:15 row_mask:0xf bank_mask:0xf
	v_mov_b32_dpp v55, v115 row_ror:15 row_mask:0xf bank_mask:0xf
	v_pk_fma_f32 v[110:111], v[82:83], v[110:111], v[86:87]
	v_pk_fma_f32 v[52:53], v[72:73], v[52:53], v[108:109]
	v_mov_b32_dpp v54, v94 row_shl:1 row_mask:0xf bank_mask:0xf
	v_mov_b32_dpp v55, v95 row_shl:1 row_mask:0xf bank_mask:0xf
	v_pk_fma_f32 v[110:111], v[94:95], v[78:79], v[110:111]
	v_pk_mul_f32 v[108:109], v[52:53], v[52:53]
	v_pk_fma_f32 v[54:55], v[74:75], v[54:55], v[110:111]
	v_pk_mul_f32 v[108:109], v[52:53], v[108:109]
	v_pk_mul_f32 v[110:111], v[54:55], v[54:55]
	v_pk_fma_f32 v[108:109], v[108:109], s[70:71], v[52:53] op_sel_hi:[1,0,1]
	v_pk_mul_f32 v[110:111], v[54:55], v[110:111]
	v_pk_mul_f32 v[108:109], v[108:109], s[72:73] op_sel_hi:[1,0]
	v_pk_fma_f32 v[110:111], v[110:111], s[70:71], v[54:55] op_sel_hi:[1,0,1]
	v_min_f32_e32 v108, 0x41e6d4ca, v108
	v_pk_mul_f32 v[110:111], v[110:111], s[72:73] op_sel_hi:[1,0]
	v_exp_f32_e32 v121, v108
	v_min_f32_e32 v108, 0x41e6d4ca, v109
	v_exp_f32_e32 v120, v108
	v_min_f32_e32 v108, 0x41e6d4ca, v110
	v_exp_f32_e32 v109, v108
	v_min_f32_e32 v108, 0x41e6d4ca, v111
	v_exp_f32_e32 v108, v108
	v_mov_b32_e32 v118, v200
	v_mov_b32_e32 v119, v200
	v_pk_mul_f32 v[50:51], v[50:51], v[118:119]
	v_pk_mul_f32 v[42:43], v[42:43], v[118:119]
	v_pk_add_f32 v[118:119], v[120:121], 1.0 op_sel_hi:[1,0]
	v_pk_add_f32 v[120:121], v[108:109], 1.0 op_sel_hi:[1,0]
	v_mul_f32_e32 v122, v119, v118
	v_mul_f32_e32 v123, v121, v120
	v_pk_mul_f32 v[110:111], v[44:45], v[198:199] op_sel_hi:[1,0]
	v_mul_f32_e32 v108, v122, v123
	v_rcp_f32_e32 v125, v108
	v_mov_b32_dpp v104, v88 row_shr:1 row_mask:0xf bank_mask:0xf
	v_mov_b32_dpp v105, v89 row_shr:1 row_mask:0xf bank_mask:0xf
	v_pk_fma_f32 v[104:105], v[64:65], v[104:105], v[68:69]
	v_mul_f32_e32 v44, v122, v125
	v_pk_mul_f32 v[120:121], v[120:121], v[44:45] op_sel_hi:[1,0]
	v_pk_mul_f32 v[108:109], v[46:47], v[198:199] op_sel_hi:[1,0]
	v_mov_b32_dpp v44, v110 row_ror:15 row_mask:0xf bank_mask:0xf
	v_mov_b32_dpp v45, v111 row_ror:15 row_mask:0xf bank_mask:0xf
	v_mov_b32_dpp v106, v90 row_shr:1 row_mask:0xf bank_mask:0xf
	v_mov_b32_dpp v107, v91 row_shr:1 row_mask:0xf bank_mask:0xf
	v_mov_b32_dpp v44, v88 row_shl:1 row_mask:0xf bank_mask:0xf
	v_mov_b32_dpp v45, v89 row_shl:1 row_mask:0xf bank_mask:0xf
	v_pk_fma_f32 v[104:105], v[88:89], v[60:61], v[104:105]
	v_mov_b32_dpp v46, v108 row_ror:15 row_mask:0xf bank_mask:0xf
	v_mov_b32_dpp v47, v109 row_ror:15 row_mask:0xf bank_mask:0xf
	v_pk_fma_f32 v[106:107], v[66:67], v[106:107], v[70:71]
	v_pk_fma_f32 v[44:45], v[56:57], v[44:45], v[104:105]
	v_mov_b32_dpp v46, v90 row_shl:1 row_mask:0xf bank_mask:0xf
	v_mov_b32_dpp v47, v91 row_shl:1 row_mask:0xf bank_mask:0xf
	v_pk_fma_f32 v[106:107], v[90:91], v[62:63], v[106:107]
	v_pk_mul_f32 v[104:105], v[44:45], v[44:45]
	v_pk_fma_f32 v[46:47], v[58:59], v[46:47], v[106:107]
	v_pk_mul_f32 v[104:105], v[44:45], v[104:105]
	v_pk_mul_f32 v[106:107], v[46:47], v[46:47]
	v_pk_fma_f32 v[104:105], v[104:105], s[70:71], v[44:45] op_sel_hi:[1,0,1]
	v_pk_mul_f32 v[106:107], v[46:47], v[106:107]
	v_pk_mul_f32 v[104:105], v[104:105], s[72:73] op_sel_hi:[1,0]
	v_pk_fma_f32 v[106:107], v[106:107], s[70:71], v[46:47] op_sel_hi:[1,0,1]
	v_min_f32_e32 v104, 0x41e6d4ca, v104
	v_mul_f32_e32 v124, v123, v125
	v_pk_mul_f32 v[106:107], v[106:107], s[72:73] op_sel_hi:[1,0]
	v_exp_f32_e32 v123, v104
	v_min_f32_e32 v104, 0x41e6d4ca, v105
	v_exp_f32_e32 v122, v104
	v_min_f32_e32 v104, 0x41e6d4ca, v106
	v_exp_f32_e32 v105, v104
	v_min_f32_e32 v104, 0x41e6d4ca, v107
	v_exp_f32_e32 v104, v104
	v_pk_mul_f32 v[106:107], v[118:119], v[124:125] op_sel_hi:[1,0]
	v_pk_add_f32 v[118:119], v[122:123], 1.0 op_sel_hi:[1,0]
	v_pk_mul_f32 v[48:49], v[48:49], v[200:201]
	v_pk_add_f32 v[104:105], v[104:105], 1.0 op_sel_hi:[1,0]
	v_mul_f32_e32 v122, v119, v118
	v_mul_f32_e32 v123, v105, v104
	v_pk_mul_f32 v[40:41], v[40:41], v[200:201]
	v_mul_f32_e32 v124, v122, v123
	v_rcp_f32_e32 v125, v124
	v_pk_mul_f32 v[106:107], v[52:53], v[106:107]
	v_add_u32_e32 v126, 0x80, v197
	v_pk_mul_f32 v[106:107], v[48:49], v[106:107]
	v_mul_f32_e32 v124, v123, v125
	v_mul_f32_e32 v122, v122, v125
	v_pk_mul_f32 v[118:119], v[118:119], v[124:125] op_sel_hi:[1,0]
	v_pk_mul_f32 v[104:105], v[104:105], v[122:123] op_sel_hi:[1,0]
	v_pk_mul_f32 v[118:119], v[44:45], v[118:119]
	v_pk_mul_f32 v[104:105], v[46:47], v[104:105]
	v_pk_mul_f32 v[118:119], v[40:41], v[118:119]
	v_pk_mul_f32 v[120:121], v[54:55], v[120:121]
	v_pk_mul_f32 v[122:123], v[42:43], v[104:105]
	v_cvt_pk_bf16_f32 v104, v106, v107
	v_cvt_pk_bf16_f32 v106, v118, v119
	v_mov_b64_e32 v[118:119], s[86:87]
	v_pk_mul_f32 v[120:121], v[50:51], v[120:121]
	v_mad_i64_i32 v[118:119], s[10:11], v126, s90, v[118:119]
	v_cvt_pk_bf16_f32 v105, v120, v121
	v_cvt_pk_bf16_f32 v107, v122, v123
	v_lshl_add_u64 v[118:119], v[192:193], 1, v[118:119]
	global_store_dwordx4 v[118:119], v[104:107], off
	s_and_saveexec_b64 s[10:11], s[42:43]
	s_cbranch_execz .LBB0_782
	s_add_u32 s24, s4, s15
	s_addc_u32 s25, s5, s16
	v_lshl_add_u64 v[104:105], v[192:193], 2, s[24:25]
	global_store_dwordx4 v[104:105], v[52:55], off
	s_nop 1
	v_add_co_u32_e32 v52, vcc, 0x2000, v104
	s_nop 1
	v_addc_co_u32_e32 v53, vcc, 0, v105, vcc
	v_add_co_u32_e32 v54, vcc, 0x5000, v104
	global_store_dwordx4 v[52:53], v[92:95], off offset:3072
	s_nop 0
	v_addc_co_u32_e32 v55, vcc, 0, v105, vcc
	global_store_dwordx4 v[54:55], v[48:51], off offset:2048
	global_store_dwordx4 v[104:105], v[44:47], off offset:16
	global_store_dwordx4 v[52:53], v[88:91], off offset:3088
	global_store_dwordx4 v[54:55], v[40:43], off offset:2064
.LBB0_782:
	s_or_b64 exec, exec, s[10:11]
	s_nop 0
	v_mov_b32_e32 v40, v198
	v_mov_b32_e32 v41, v198
	v_pk_mul_f32 v[44:45], v[22:23], v[40:41]
	v_pk_mul_f32 v[40:41], v[18:19], v[40:41]
	v_pk_mul_f32 v[18:19], v[24:25], v[196:197] op_sel_hi:[1,0]
	v_mov_b32_e32 v24, v194
	v_mov_b32_e32 v25, v194
	v_pk_mul_f32 v[6:7], v[6:7], v[24:25]
	v_pk_mul_f32 v[2:3], v[2:3], v[24:25]
	v_mov_b32_e32 v199, v198
	v_mov_b32_dpp v24, v92 row_ror:1 row_mask:0xf bank_mask:0xf
	v_mov_b32_dpp v25, v93 row_ror:1 row_mask:0xf bank_mask:0xf
	v_pk_mul_f32 v[42:43], v[16:17], v[198:199]
	v_pk_mul_f32 v[22:23], v[28:29], v[196:197] op_sel_hi:[1,0]
	v_pk_mul_f32 v[16:17], v[26:27], v[196:197] op_sel_hi:[1,0]
	v_mov_b32_dpp v24, v116 row_shr:1 row_mask:0xf bank_mask:0xf
	v_mov_b32_dpp v25, v117 row_shr:1 row_mask:0xf bank_mask:0xf
	v_mov_b32_dpp v26, v94 row_ror:1 row_mask:0xf bank_mask:0xf
	v_mov_b32_dpp v27, v95 row_ror:1 row_mask:0xf bank_mask:0xf
	v_mov_b32_dpp v28, v22 row_ror:15 row_mask:0xf bank_mask:0xf
	v_mov_b32_dpp v29, v23 row_ror:15 row_mask:0xf bank_mask:0xf
	v_pk_fma_f32 v[24:25], v[80:81], v[24:25], v[84:85]
	v_pk_mul_f32 v[46:47], v[20:21], v[198:199]
	v_pk_mul_f32 v[20:21], v[30:31], v[196:197] op_sel_hi:[1,0]
	v_mov_b32_dpp v26, v114 row_shr:1 row_mask:0xf bank_mask:0xf
	v_mov_b32_dpp v27, v115 row_shr:1 row_mask:0xf bank_mask:0xf
	v_mov_b32_dpp v28, v116 row_shl:1 row_mask:0xf bank_mask:0xf
	v_mov_b32_dpp v29, v117 row_shl:1 row_mask:0xf bank_mask:0xf
	v_pk_fma_f32 v[24:25], v[116:117], v[76:77], v[24:25]
	v_mov_b32_dpp v30, v20 row_ror:15 row_mask:0xf bank_mask:0xf
	v_mov_b32_dpp v31, v21 row_ror:15 row_mask:0xf bank_mask:0xf
	v_pk_fma_f32 v[26:27], v[82:83], v[26:27], v[86:87]
	v_pk_fma_f32 v[24:25], v[72:73], v[28:29], v[24:25]
	v_mov_b32_dpp v30, v114 row_shl:1 row_mask:0xf bank_mask:0xf
	v_mov_b32_dpp v31, v115 row_shl:1 row_mask:0xf bank_mask:0xf
	v_pk_fma_f32 v[26:27], v[114:115], v[78:79], v[26:27]
	v_pk_mul_f32 v[28:29], v[24:25], v[24:25]
	v_pk_fma_f32 v[26:27], v[74:75], v[30:31], v[26:27]
	v_pk_mul_f32 v[28:29], v[24:25], v[28:29]
	v_pk_mul_f32 v[30:31], v[26:27], v[26:27]
	v_pk_fma_f32 v[28:29], v[28:29], s[70:71], v[24:25] op_sel_hi:[1,0,1]
	v_pk_mul_f32 v[30:31], v[26:27], v[30:31]
	v_pk_mul_f32 v[28:29], v[28:29], s[72:73] op_sel_hi:[1,0]
	v_pk_fma_f32 v[30:31], v[30:31], s[70:71], v[26:27] op_sel_hi:[1,0,1]
	v_min_f32_e32 v28, 0x41e6d4ca, v28
	v_pk_mul_f32 v[30:31], v[30:31], s[72:73] op_sel_hi:[1,0]
	v_exp_f32_e32 v49, v28
	v_min_f32_e32 v28, 0x41e6d4ca, v29
	v_exp_f32_e32 v48, v28
	v_min_f32_e32 v28, 0x41e6d4ca, v30
	v_exp_f32_e32 v29, v28
	v_min_f32_e32 v28, 0x41e6d4ca, v31
	v_exp_f32_e32 v28, v28
	v_pk_add_f32 v[30:31], v[48:49], 1.0 op_sel_hi:[1,0]
	v_add_u32_e32 v52, 0x90, v197
	v_pk_add_f32 v[28:29], v[28:29], 1.0 op_sel_hi:[1,0]
	v_mul_f32_e32 v48, v31, v30
	v_mul_f32_e32 v49, v29, v28
	v_pk_mul_f32 v[12:13], v[12:13], v[196:197] op_sel_hi:[1,0]
	v_mul_f32_e32 v50, v48, v49
	v_rcp_f32_e32 v51, v50
	v_pk_mul_f32 v[14:15], v[14:15], v[196:197] op_sel_hi:[1,0]
	v_pk_mul_f32 v[10:11], v[10:11], v[196:197] op_sel_hi:[1,0]
	v_pk_mul_f32 v[8:9], v[8:9], v[196:197] op_sel_hi:[1,0]
	v_mul_f32_e32 v48, v48, v51
	v_pk_mul_f32 v[28:29], v[28:29], v[48:49] op_sel_hi:[1,0]
	v_mul_f32_e32 v50, v49, v51
	v_pk_mul_f32 v[26:27], v[26:27], v[28:29]
	v_pk_mul_f32 v[30:31], v[30:31], v[50:51] op_sel_hi:[1,0]
	v_pk_mul_f32 v[28:29], v[44:45], v[26:27]
	v_pk_mul_f32 v[24:25], v[24:25], v[30:31]
	v_mov_b32_dpp v26, v88 row_ror:1 row_mask:0xf bank_mask:0xf
	v_mov_b32_dpp v27, v89 row_ror:1 row_mask:0xf bank_mask:0xf
	s_nop 0
	v_mov_b32_dpp v26, v110 row_shr:1 row_mask:0xf bank_mask:0xf
	v_mov_b32_dpp v27, v111 row_shr:1 row_mask:0xf bank_mask:0xf
	v_mov_b32_dpp v30, v90 row_ror:1 row_mask:0xf bank_mask:0xf
	v_mov_b32_dpp v31, v91 row_ror:1 row_mask:0xf bank_mask:0xf
	v_mov_b32_dpp v44, v18 row_ror:15 row_mask:0xf bank_mask:0xf
	v_mov_b32_dpp v45, v19 row_ror:15 row_mask:0xf bank_mask:0xf
	v_pk_fma_f32 v[26:27], v[64:65], v[26:27], v[68:69]
	v_pk_mul_f32 v[24:25], v[46:47], v[24:25]
	v_mov_b32_dpp v30, v108 row_shr:1 row_mask:0xf bank_mask:0xf
	v_mov_b32_dpp v31, v109 row_shr:1 row_mask:0xf bank_mask:0xf
	v_mov_b32_dpp v44, v110 row_shl:1 row_mask:0xf bank_mask:0xf
	v_mov_b32_dpp v45, v111 row_shl:1 row_mask:0xf bank_mask:0xf
	v_pk_fma_f32 v[26:27], v[110:111], v[60:61], v[26:27]
	v_mov_b32_dpp v46, v16 row_ror:15 row_mask:0xf bank_mask:0xf
	v_mov_b32_dpp v47, v17 row_ror:15 row_mask:0xf bank_mask:0xf
	v_pk_fma_f32 v[30:31], v[66:67], v[30:31], v[70:71]
	v_pk_fma_f32 v[26:27], v[56:57], v[44:45], v[26:27]
	v_mov_b32_dpp v46, v108 row_shl:1 row_mask:0xf bank_mask:0xf
	v_mov_b32_dpp v47, v109 row_shl:1 row_mask:0xf bank_mask:0xf
	v_pk_fma_f32 v[30:31], v[108:109], v[62:63], v[30:31]
	v_pk_mul_f32 v[44:45], v[26:27], v[26:27]
	v_pk_fma_f32 v[30:31], v[58:59], v[46:47], v[30:31]
	v_pk_mul_f32 v[44:45], v[26:27], v[44:45]
	v_pk_mul_f32 v[46:47], v[30:31], v[30:31]
	v_pk_fma_f32 v[44:45], v[44:45], s[70:71], v[26:27] op_sel_hi:[1,0,1]
	v_pk_mul_f32 v[46:47], v[30:31], v[46:47]
	v_pk_mul_f32 v[44:45], v[44:45], s[72:73] op_sel_hi:[1,0]
	v_pk_fma_f32 v[46:47], v[46:47], s[70:71], v[30:31] op_sel_hi:[1,0,1]
	v_min_f32_e32 v44, 0x41e6d4ca, v44
	v_pk_mul_f32 v[46:47], v[46:47], s[72:73] op_sel_hi:[1,0]
	v_exp_f32_e32 v49, v44
	v_min_f32_e32 v44, 0x41e6d4ca, v45
	v_exp_f32_e32 v48, v44
	v_min_f32_e32 v44, 0x41e6d4ca, v46
	v_exp_f32_e32 v45, v44
	v_min_f32_e32 v44, 0x41e6d4ca, v47
	v_exp_f32_e32 v44, v44
	v_pk_add_f32 v[46:47], v[48:49], 1.0 op_sel_hi:[1,0]
	v_mov_b32_dpp v100, v36 row_shl:1 row_mask:0xf bank_mask:0xf
	v_pk_add_f32 v[44:45], v[44:45], 1.0 op_sel_hi:[1,0]
	v_mul_f32_e32 v48, v47, v46
	v_mul_f32_e32 v49, v45, v44
	v_mov_b32_dpp v101, v37 row_shl:1 row_mask:0xf bank_mask:0xf
	v_mul_f32_e32 v50, v48, v49
	v_rcp_f32_e32 v51, v50
	v_mov_b32_dpp v102, v38 row_shl:1 row_mask:0xf bank_mask:0xf
	v_mov_b32_dpp v103, v39 row_shl:1 row_mask:0xf bank_mask:0xf
	v_pk_mul_f32 v[4:5], v[4:5], v[194:195]
	v_mul_f32_e32 v50, v49, v51
	v_mul_f32_e32 v48, v48, v51
	v_pk_mul_f32 v[44:45], v[44:45], v[48:49] op_sel_hi:[1,0]
	v_pk_mul_f32 v[46:47], v[46:47], v[50:51] op_sel_hi:[1,0]
	v_pk_mul_f32 v[30:31], v[30:31], v[44:45]
	v_pk_mul_f32 v[26:27], v[26:27], v[46:47]
	v_pk_mul_f32 v[30:31], v[40:41], v[30:31]
	v_pk_mul_f32 v[40:41], v[42:43], v[26:27]
	v_cvt_pk_bf16_f32 v26, v24, v25
	v_mov_b64_e32 v[24:25], s[86:87]
	v_cvt_pk_bf16_f32 v27, v28, v29
	v_cvt_pk_bf16_f32 v29, v30, v31
	v_mad_i64_i32 v[30:31], s[10:11], v52, s90, v[24:25]
	v_cvt_pk_bf16_f32 v28, v40, v41
	v_lshl_add_u64 v[30:31], v[30:31], 0, v[112:113]
	global_store_dwordx4 v[30:31], v[26:29], off
	s_nop 0
	s_nop 0
	v_mov_b32_dpp v26, v116 row_ror:1 row_mask:0xf bank_mask:0xf
	v_mov_b32_dpp v27, v117 row_ror:1 row_mask:0xf bank_mask:0xf
	s_nop 0
	v_mov_b32_dpp v26, v22 row_shr:1 row_mask:0xf bank_mask:0xf
	v_mov_b32_dpp v27, v23 row_shr:1 row_mask:0xf bank_mask:0xf
	v_mov_b32_dpp v28, v114 row_ror:1 row_mask:0xf bank_mask:0xf
	v_mov_b32_dpp v29, v115 row_ror:1 row_mask:0xf bank_mask:0xf
	v_mov_b32_dpp v30, v36 row_ror:15 row_mask:0xf bank_mask:0xf
	v_mov_b32_dpp v31, v37 row_ror:15 row_mask:0xf bank_mask:0xf
	v_pk_fma_f32 v[26:27], v[80:81], v[26:27], v[84:85]
	v_mov_b32_dpp v28, v20 row_shr:1 row_mask:0xf bank_mask:0xf
	v_mov_b32_dpp v29, v21 row_shr:1 row_mask:0xf bank_mask:0xf
	v_mov_b32_dpp v30, v22 row_shl:1 row_mask:0xf bank_mask:0xf
	v_mov_b32_dpp v31, v23 row_shl:1 row_mask:0xf bank_mask:0xf
	v_pk_fma_f32 v[26:27], v[22:23], v[76:77], v[26:27]
	v_mov_b32_dpp v40, v38 row_ror:15 row_mask:0xf bank_mask:0xf
	v_mov_b32_dpp v41, v39 row_ror:15 row_mask:0xf bank_mask:0xf
	v_pk_fma_f32 v[28:29], v[82:83], v[28:29], v[86:87]
	v_pk_fma_f32 v[26:27], v[72:73], v[30:31], v[26:27]
	v_mov_b32_dpp v40, v20 row_shl:1 row_mask:0xf bank_mask:0xf
	v_mov_b32_dpp v41, v21 row_shl:1 row_mask:0xf bank_mask:0xf
	v_pk_fma_f32 v[28:29], v[20:21], v[78:79], v[28:29]
	v_pk_mul_f32 v[30:31], v[26:27], v[26:27]
	v_pk_fma_f32 v[28:29], v[74:75], v[40:41], v[28:29]
	v_pk_mul_f32 v[30:31], v[26:27], v[30:31]
	v_pk_mul_f32 v[40:41], v[28:29], v[28:29]
	v_pk_fma_f32 v[30:31], v[30:31], s[70:71], v[26:27] op_sel_hi:[1,0,1]
	v_pk_mul_f32 v[40:41], v[28:29], v[40:41]
	v_pk_mul_f32 v[30:31], v[30:31], s[72:73] op_sel_hi:[1,0]
	v_pk_fma_f32 v[40:41], v[40:41], s[70:71], v[28:29] op_sel_hi:[1,0,1]
	v_min_f32_e32 v30, 0x41e6d4ca, v30
	v_pk_mul_f32 v[40:41], v[40:41], s[72:73] op_sel_hi:[1,0]
	v_exp_f32_e32 v43, v30
	v_min_f32_e32 v30, 0x41e6d4ca, v31
	v_exp_f32_e32 v42, v30
	v_min_f32_e32 v30, 0x41e6d4ca, v40
	v_exp_f32_e32 v31, v30
	v_min_f32_e32 v30, 0x41e6d4ca, v41
	v_exp_f32_e32 v30, v30
	v_pk_add_f32 v[40:41], v[42:43], 1.0 op_sel_hi:[1,0]
	v_add_u32_e32 v46, 0xa0, v197
	v_pk_add_f32 v[30:31], v[30:31], 1.0 op_sel_hi:[1,0]
	v_mul_f32_e32 v42, v41, v40
	v_mul_f32_e32 v43, v31, v30
	v_mov_b32_dpp v96, v32 row_shl:1 row_mask:0xf bank_mask:0xf
	v_mul_f32_e32 v44, v42, v43
	v_rcp_f32_e32 v45, v44
	v_mov_b32_dpp v97, v33 row_shl:1 row_mask:0xf bank_mask:0xf
	v_mov_b32_dpp v98, v34 row_shl:1 row_mask:0xf bank_mask:0xf
	v_mov_b32_dpp v99, v35 row_shl:1 row_mask:0xf bank_mask:0xf
	v_mul_f32_e32 v44, v43, v45
	v_pk_mul_f32 v[40:41], v[40:41], v[44:45] op_sel_hi:[1,0]
	v_mul_f32_e32 v42, v42, v45
	v_pk_mul_f32 v[26:27], v[26:27], v[40:41]
	v_pk_mul_f32 v[30:31], v[30:31], v[42:43] op_sel_hi:[1,0]
	v_pk_mul_f32 v[12:13], v[12:13], v[26:27]
	v_pk_mul_f32 v[28:29], v[28:29], v[30:31]
	v_mov_b32_dpp v26, v110 row_ror:1 row_mask:0xf bank_mask:0xf
	v_mov_b32_dpp v27, v111 row_ror:1 row_mask:0xf bank_mask:0xf
	v_pk_mul_f32 v[14:15], v[14:15], v[28:29]
	v_mov_b32_dpp v26, v18 row_shr:1 row_mask:0xf bank_mask:0xf
	v_mov_b32_dpp v27, v19 row_shr:1 row_mask:0xf bank_mask:0xf
	v_mov_b32_dpp v28, v108 row_ror:1 row_mask:0xf bank_mask:0xf
	v_mov_b32_dpp v29, v109 row_ror:1 row_mask:0xf bank_mask:0xf
	v_mov_b32_dpp v30, v32 row_ror:15 row_mask:0xf bank_mask:0xf
	v_mov_b32_dpp v31, v33 row_ror:15 row_mask:0xf bank_mask:0xf
	v_pk_fma_f32 v[26:27], v[64:65], v[26:27], v[68:69]
	v_mov_b32_dpp v28, v16 row_shr:1 row_mask:0xf bank_mask:0xf
	v_mov_b32_dpp v29, v17 row_shr:1 row_mask:0xf bank_mask:0xf
	v_mov_b32_dpp v30, v18 row_shl:1 row_mask:0xf bank_mask:0xf
	v_mov_b32_dpp v31, v19 row_shl:1 row_mask:0xf bank_mask:0xf
	v_pk_fma_f32 v[26:27], v[18:19], v[60:61], v[26:27]
	v_mov_b32_dpp v40, v34 row_ror:15 row_mask:0xf bank_mask:0xf
	v_mov_b32_dpp v41, v35 row_ror:15 row_mask:0xf bank_mask:0xf
	v_pk_fma_f32 v[28:29], v[66:67], v[28:29], v[70:71]
	v_pk_fma_f32 v[26:27], v[56:57], v[30:31], v[26:27]
	v_mov_b32_dpp v40, v16 row_shl:1 row_mask:0xf bank_mask:0xf
	v_mov_b32_dpp v41, v17 row_shl:1 row_mask:0xf bank_mask:0xf
	v_pk_fma_f32 v[28:29], v[16:17], v[62:63], v[28:29]
	v_pk_mul_f32 v[30:31], v[26:27], v[26:27]
	v_pk_fma_f32 v[28:29], v[58:59], v[40:41], v[28:29]
	v_pk_mul_f32 v[30:31], v[26:27], v[30:31]
	v_pk_mul_f32 v[40:41], v[28:29], v[28:29]
	v_pk_fma_f32 v[30:31], v[30:31], s[70:71], v[26:27] op_sel_hi:[1,0,1]
	v_pk_mul_f32 v[40:41], v[28:29], v[40:41]
	v_pk_mul_f32 v[30:31], v[30:31], s[72:73] op_sel_hi:[1,0]
	v_pk_fma_f32 v[40:41], v[40:41], s[70:71], v[28:29] op_sel_hi:[1,0,1]
	v_min_f32_e32 v30, 0x41e6d4ca, v30
	v_pk_mul_f32 v[40:41], v[40:41], s[72:73] op_sel_hi:[1,0]
	v_exp_f32_e32 v43, v30
	v_min_f32_e32 v30, 0x41e6d4ca, v31
	v_exp_f32_e32 v42, v30
	v_min_f32_e32 v30, 0x41e6d4ca, v40
	v_exp_f32_e32 v31, v30
	v_min_f32_e32 v30, 0x41e6d4ca, v41
	v_exp_f32_e32 v30, v30
	v_pk_add_f32 v[40:41], v[42:43], 1.0 op_sel_hi:[1,0]
	v_pk_mul_f32 v[0:1], v[0:1], v[194:195]
	v_pk_add_f32 v[30:31], v[30:31], 1.0 op_sel_hi:[1,0]
	v_mul_f32_e32 v42, v41, v40
	v_mul_f32_e32 v43, v31, v30
	s_nop 0
	v_mul_f32_e32 v44, v42, v43
	v_rcp_f32_e32 v45, v44
	s_nop 0
	v_mul_f32_e32 v44, v43, v45
	v_mul_f32_e32 v42, v42, v45
	v_pk_mul_f32 v[30:31], v[30:31], v[42:43] op_sel_hi:[1,0]
	v_pk_mul_f32 v[40:41], v[40:41], v[44:45] op_sel_hi:[1,0]
	v_pk_mul_f32 v[28:29], v[28:29], v[30:31]
	v_pk_mul_f32 v[26:27], v[26:27], v[40:41]
	v_pk_mul_f32 v[28:29], v[10:11], v[28:29]
	v_pk_mul_f32 v[10:11], v[8:9], v[26:27]
	v_cvt_pk_bf16_f32 v8, v12, v13
	v_mad_i64_i32 v[12:13], s[10:11], v46, s90, v[24:25]
	v_cvt_pk_bf16_f32 v9, v14, v15
	v_cvt_pk_bf16_f32 v10, v10, v11
	v_cvt_pk_bf16_f32 v11, v28, v29
	v_lshl_add_u64 v[12:13], v[12:13], 0, v[112:113]
	global_store_dwordx4 v[12:13], v[8:11], off
	v_add_u32_e32 v30, 0xb0, v197
	s_nop 0
	v_mov_b32_dpp v8, v22 row_ror:1 row_mask:0xf bank_mask:0xf
	v_mov_b32_dpp v9, v23 row_ror:1 row_mask:0xf bank_mask:0xf
	s_nop 0
	v_mov_b32_dpp v8, v36 row_shr:1 row_mask:0xf bank_mask:0xf
	v_mov_b32_dpp v9, v37 row_shr:1 row_mask:0xf bank_mask:0xf
	v_mov_b32_dpp v10, v20 row_ror:1 row_mask:0xf bank_mask:0xf
	v_mov_b32_dpp v11, v21 row_ror:1 row_mask:0xf bank_mask:0xf
	v_pk_fma_f32 v[8:9], v[80:81], v[8:9], v[84:85]
	v_mov_b32_dpp v10, v38 row_shr:1 row_mask:0xf bank_mask:0xf
	v_mov_b32_dpp v11, v39 row_shr:1 row_mask:0xf bank_mask:0xf
	v_pk_fma_f32 v[8:9], v[36:37], v[76:77], v[8:9]
	v_pk_fma_f32 v[10:11], v[82:83], v[10:11], v[86:87]
	v_pk_fma_f32 v[8:9], v[72:73], v[100:101], v[8:9]
	v_pk_fma_f32 v[10:11], v[38:39], v[78:79], v[10:11]
	v_pk_mul_f32 v[12:13], v[8:9], v[8:9]
	v_pk_fma_f32 v[10:11], v[74:75], v[102:103], v[10:11]
	v_pk_mul_f32 v[12:13], v[8:9], v[12:13]
	v_pk_mul_f32 v[14:15], v[10:11], v[10:11]
	v_pk_fma_f32 v[12:13], v[12:13], s[70:71], v[8:9] op_sel_hi:[1,0,1]
	v_pk_mul_f32 v[14:15], v[10:11], v[14:15]
	v_pk_mul_f32 v[12:13], v[12:13], s[72:73] op_sel_hi:[1,0]
	v_pk_fma_f32 v[14:15], v[14:15], s[70:71], v[10:11] op_sel_hi:[1,0,1]
	v_min_f32_e32 v12, 0x41e6d4ca, v12
	v_pk_mul_f32 v[14:15], v[14:15], s[72:73] op_sel_hi:[1,0]
	v_exp_f32_e32 v21, v12
	v_min_f32_e32 v12, 0x41e6d4ca, v13
	v_exp_f32_e32 v20, v12
	v_min_f32_e32 v12, 0x41e6d4ca, v14
	v_exp_f32_e32 v13, v12
	v_min_f32_e32 v12, 0x41e6d4ca, v15
	v_exp_f32_e32 v12, v12
	v_pk_add_f32 v[14:15], v[20:21], 1.0 op_sel_hi:[1,0]
	v_pk_add_f32 v[12:13], v[12:13], 1.0 op_sel_hi:[1,0]
	v_mul_f32_e32 v20, v15, v14
	v_mul_f32_e32 v21, v13, v12
	s_nop 0
	v_mul_f32_e32 v22, v20, v21
	v_rcp_f32_e32 v23, v22
	s_nop 0
	v_mul_f32_e32 v20, v20, v23
	v_pk_mul_f32 v[12:13], v[12:13], v[20:21] op_sel_hi:[1,0]
	v_mul_f32_e32 v22, v21, v23
	v_pk_mul_f32 v[12:13], v[10:11], v[12:13]
	v_pk_mul_f32 v[14:15], v[14:15], v[22:23] op_sel_hi:[1,0]
	v_pk_mul_f32 v[20:21], v[6:7], v[12:13]
	v_pk_mul_f32 v[14:15], v[8:9], v[14:15]
	v_mov_b32_dpp v12, v18 row_ror:1 row_mask:0xf bank_mask:0xf
	v_mov_b32_dpp v13, v19 row_ror:1 row_mask:0xf bank_mask:0xf
	v_pk_mul_f32 v[22:23], v[4:5], v[14:15]
	v_mov_b32_dpp v12, v32 row_shr:1 row_mask:0xf bank_mask:0xf
	v_mov_b32_dpp v13, v33 row_shr:1 row_mask:0xf bank_mask:0xf
	v_mov_b32_dpp v14, v16 row_ror:1 row_mask:0xf bank_mask:0xf
	v_mov_b32_dpp v15, v17 row_ror:1 row_mask:0xf bank_mask:0xf
	v_pk_fma_f32 v[12:13], v[64:65], v[12:13], v[68:69]
	v_mov_b32_dpp v14, v34 row_shr:1 row_mask:0xf bank_mask:0xf
	v_mov_b32_dpp v15, v35 row_shr:1 row_mask:0xf bank_mask:0xf
	v_pk_fma_f32 v[12:13], v[32:33], v[60:61], v[12:13]
	v_pk_fma_f32 v[14:15], v[66:67], v[14:15], v[70:71]
	v_pk_fma_f32 v[12:13], v[56:57], v[96:97], v[12:13]
	v_pk_fma_f32 v[14:15], v[34:35], v[62:63], v[14:15]
	v_pk_mul_f32 v[16:17], v[12:13], v[12:13]
	v_pk_fma_f32 v[14:15], v[58:59], v[98:99], v[14:15]
	v_pk_mul_f32 v[16:17], v[12:13], v[16:17]
	v_pk_mul_f32 v[18:19], v[14:15], v[14:15]
	v_pk_fma_f32 v[16:17], v[16:17], s[70:71], v[12:13] op_sel_hi:[1,0,1]
	v_pk_mul_f32 v[18:19], v[14:15], v[18:19]
	v_pk_mul_f32 v[16:17], v[16:17], s[72:73] op_sel_hi:[1,0]
	v_pk_fma_f32 v[18:19], v[18:19], s[70:71], v[14:15] op_sel_hi:[1,0,1]
	v_min_f32_e32 v16, 0x41e6d4ca, v16
	v_pk_mul_f32 v[18:19], v[18:19], s[72:73] op_sel_hi:[1,0]
	v_exp_f32_e32 v27, v16
	v_min_f32_e32 v16, 0x41e6d4ca, v17
	v_exp_f32_e32 v26, v16
	v_min_f32_e32 v16, 0x41e6d4ca, v18
	v_exp_f32_e32 v17, v16
	v_min_f32_e32 v16, 0x41e6d4ca, v19
	v_exp_f32_e32 v16, v16
	v_pk_add_f32 v[18:19], v[26:27], 1.0 op_sel_hi:[1,0]
	v_pk_add_f32 v[16:17], v[16:17], 1.0 op_sel_hi:[1,0]
	v_mul_f32_e32 v26, v19, v18
	v_mul_f32_e32 v27, v17, v16
	s_nop 0
	v_mul_f32_e32 v28, v26, v27
	v_rcp_f32_e32 v29, v28
	s_nop 0
	v_mul_f32_e32 v28, v27, v29
	v_mul_f32_e32 v26, v26, v29
	v_pk_mul_f32 v[16:17], v[16:17], v[26:27] op_sel_hi:[1,0]
	v_pk_mul_f32 v[18:19], v[18:19], v[28:29] op_sel_hi:[1,0]
	v_pk_mul_f32 v[16:17], v[14:15], v[16:17]
	v_pk_mul_f32 v[18:19], v[12:13], v[18:19]
	v_pk_mul_f32 v[26:27], v[2:3], v[16:17]
	v_pk_mul_f32 v[18:19], v[0:1], v[18:19]
	v_cvt_pk_bf16_f32 v17, v20, v21
	v_mad_i64_i32 v[20:21], s[10:11], v30, s90, v[24:25]
	v_cvt_pk_bf16_f32 v16, v22, v23
	v_cvt_pk_bf16_f32 v18, v18, v19
	v_cvt_pk_bf16_f32 v19, v26, v27
	v_lshl_add_u64 v[20:21], v[20:21], 0, v[112:113]
	global_store_dwordx4 v[20:21], v[16:19], off
	s_and_saveexec_b64 s[10:11], s[64:65]
	s_cbranch_execz .LBB0_784
	s_add_u32 s14, s4, s14
	s_addc_u32 s15, s5, s12
	v_lshl_add_u64 v[16:17], v[192:193], 2, s[14:15]
	global_store_dwordx4 v[16:17], v[8:11], off
	s_nop 1
	v_add_co_u32_e32 v8, vcc, 0x2000, v16
	s_nop 1
	v_addc_co_u32_e32 v9, vcc, 0, v17, vcc
	v_add_co_u32_e32 v10, vcc, 0x5000, v16
	global_store_dwordx4 v[8:9], v[36:39], off offset:3072
	s_nop 0
	v_addc_co_u32_e32 v11, vcc, 0, v17, vcc
	global_store_dwordx4 v[10:11], v[4:7], off offset:2048
	global_store_dwordx4 v[16:17], v[12:15], off offset:16
	global_store_dwordx4 v[8:9], v[32:35], off offset:3088
	global_store_dwordx4 v[10:11], v[0:3], off offset:2064
